# v45: tagged-slot exchange with a single-lane probe stage before the 32-row poll (less polling traffic while partners still compute)
# speedup vs baseline: 1.0049x; 1.0049x over previous
.LBB0_628:
	s_or_b64 exec, exec, s[0:1]
	s_lshl_b32 s0, s11, 6
	s_add_i32 s28, s39, s0
	v_and_b32_e32 v0, 31, v146
	s_lshl_b32 s3, s28, 8
	v_lshl_or_b32 v226, s19, 5, v0
	v_add_u32_e32 v0, s3, v226
	s_waitcnt lgkmcnt(0)
	v_ashrrev_i32_e32 v1, 31, v0
	s_waitcnt lgkmcnt(0)
	s_barrier
	v_lshlrev_b64 v[0:1], 5, v[0:1]
	v_lshl_add_u64 v[174:175], s[16:17], 0, v[0:1]
	s_mov_b64 s[0:1], 0x9000000
	v_lshl_add_u64 v[0:1], v[174:175], 0, s[0:1]
	v_cmp_gt_u32_e64 s[4:5], 32, v132
	v_cmp_eq_u32_e64 s[8:9], 0, v132
	v_readlane_b32 s55, v255, 46
	s_lshl_b32 s34, s10, 6
	s_cmp_lt_u32 s2, 64
	s_cselect_b64 s[0:1], -1, 0
	s_lshr_b32 s11, s34, 5
	s_add_i32 s11, s11, 0x7fa5c301
	s_and_saveexec_b64 s[22:23], s[4:5]
	v_lshl_add_u32 v133, v226, 4, 16
	ds_read_b128 v[134:137], v133
	s_ashr_i32 s19, s18, 31
	s_waitcnt lgkmcnt(0)
	v_mov_b32_e32 v138, v135
	v_mov_b32_e32 v139, v136
	v_mov_b32_e32 v135, v137
	v_pk_add_f32 v[134:135], v[138:139], v[134:135]
	v_lshl_add_u64 v[136:137], s[18:19], 3, v[0:1]
	s_nop 0
	v_pk_add_f32 v[134:135], v[134:135], v[134:135] op_sel:[0,1] op_sel_hi:[1,0]
	s_nop 0
	v_mov_b32_e32 v135, s11
	global_store_dwordx2 v[136:137], v[134:135], off sc1
	s_mov_b32 s19, 0x100000
	s_mov_b64 exec, 1
.Lxch1_probe:
	global_load_dwordx4 v[136:139], v[0:1], off sc1
	global_load_dwordx4 v[140:143], v[0:1], off offset:16 sc1
	s_waitcnt vmcnt(0)
	v_cmp_ne_u32_e32 vcc, s11, v137
	v_cmp_ne_u32_e64 s[24:25], s11, v139
	s_or_b64 s[24:25], s[24:25], vcc
	v_cmp_ne_u32_e32 vcc, s11, v141
	s_or_b64 s[24:25], s[24:25], vcc
	v_cmp_ne_u32_e32 vcc, s11, v143
	s_or_b64 s[24:25], s[24:25], vcc
	s_and_b64 s[24:25], s[24:25], exec
	s_cbranch_scc0 .Lxch1_full
	s_sub_i32 s19, s19, 1
	s_cmp_lt_i32 s19, 1
	s_cbranch_scc1 .Lxch1_full
	s_sleep 1
	s_branch .Lxch1_probe
.Lxch1_full:
	s_and_b64 exec, s[22:23], s[4:5]

.LBB0_708:
	s_or_b64 exec, exec, s[10:11]
	s_waitcnt lgkmcnt(0)
	s_barrier
	s_mov_b64 s[2:3], 0x9100000
	v_lshl_add_u64 v[4:5], v[174:175], 0, s[2:3]
	s_lshr_b32 s2, s34, 5
	s_add_i32 s2, s2, 0x7fa5c302
	s_and_saveexec_b64 s[6:7], s[4:5]
	v_lshl_add_u32 v3, v226, 4, 16
	ds_read_b128 v[6:9], v3
	s_ashr_i32 s19, s18, 31
	s_waitcnt lgkmcnt(0)
	v_mov_b32_e32 v10, v7
	v_mov_b32_e32 v11, v8
	v_mov_b32_e32 v7, v9
	v_pk_add_f32 v[6:7], v[10:11], v[6:7]
	v_lshl_add_u64 v[8:9], s[18:19], 3, v[4:5]
	s_nop 0
	v_pk_add_f32 v[6:7], v[6:7], v[6:7] op_sel:[0,1] op_sel_hi:[1,0]
	s_nop 0
	v_mov_b32_e32 v7, s2
	global_store_dwordx2 v[8:9], v[6:7], off sc1
	s_mov_b32 s3, 0x100000
	s_mov_b64 exec, 1
.Lxch2_probe:
	global_load_dwordx4 v[8:11], v[4:5], off sc1
	global_load_dwordx4 v[12:15], v[4:5], off offset:16 sc1
	s_waitcnt vmcnt(0)
	v_cmp_ne_u32_e32 vcc, s2, v9
	v_cmp_ne_u32_e64 s[0:1], s2, v11
	s_or_b64 s[0:1], s[0:1], vcc
	v_cmp_ne_u32_e32 vcc, s2, v13
	s_or_b64 s[0:1], s[0:1], vcc
	v_cmp_ne_u32_e32 vcc, s2, v15
	s_or_b64 s[0:1], s[0:1], vcc
	s_and_b64 s[0:1], s[0:1], exec
	s_cbranch_scc0 .Lxch2_full
	s_sub_i32 s3, s3, 1
	s_cmp_lt_i32 s3, 1
	s_cbranch_scc1 .Lxch2_full
	s_sleep 1
	s_branch .Lxch2_probe
.Lxch2_full:
	s_and_b64 exec, s[6:7], s[4:5]
